# PEER query GEMM first half (load trips): next-step LDS writes issued one per MFMA from the 7th MFMA on instead of a block before the barrier; lgkmcnt recounted for the mixed queue
# speedup vs baseline: 1.0040x; 1.0040x over previous
.LBB0_1849:
	s_add_i32 s3, s3, 2
	s_cmp_lt_u32 s3, 14
	s_cselect_b64 s[8:9], -1, 0
	s_cmp_gt_u32 s3, 13
	s_cselect_b64 s[6:7], -1, 0
	s_and_b64 vcc, exec, s[6:7]
	v_lshl_add_u64 v[180:181], v[162:163], 0, v[32:33]
	v_lshl_add_u64 v[184:185], v[178:179], 0, v[32:33]
	v_lshl_add_u64 v[182:183], v[172:173], 0, v[32:33]
	s_cbranch_vccnz .LBB0_1851
	v_add_co_u32_e32 v74, vcc, 0x10000, v180
	v_lshl_add_u64 v[66:67], v[174:175], 0, v[32:33]
	s_nop 0
	v_addc_co_u32_e32 v75, vcc, 0, v181, vcc
	v_add_co_u32_e32 v78, vcc, 0x20000, v180
	v_lshl_add_u64 v[70:71], v[176:177], 0, v[32:33]
	s_nop 0
	v_addc_co_u32_e32 v79, vcc, 0, v181, vcc
	v_add_co_u32_e32 v90, vcc, 0x30000, v180
	global_load_dwordx4 v[66:69], v[66:67], off
	s_nop 0
	v_addc_co_u32_e32 v91, vcc, 0, v181, vcc
	global_load_dwordx4 v[70:73], v[70:71], off
	s_nop 0
	global_load_dwordx4 v[86:89], v[184:185], off
	s_nop 0
	global_load_dwordx4 v[74:77], v[74:75], off offset:256
	s_nop 0
	global_load_dwordx4 v[82:85], v[78:79], off offset:256
	global_load_dwordx4 v[94:97], v[182:183], off offset:-128
	s_nop 0
	global_load_dwordx4 v[78:81], v[180:181], off offset:256
	s_nop 0
	global_load_dwordx4 v[90:93], v[90:91], off offset:256
	s_setprio 2
	ds_read_b128 v[194:197], v164 offset:36864
	ds_read_b128 v[224:227], v189
	ds_read_b128 v[228:231], v189 offset:4608
	ds_read_b128 v[232:235], v189 offset:9216
	ds_read_b128 v[236:239], v189 offset:13824
	s_cmp_gt_u32 s3, 12
	ds_read_b128 v[240:243], v164 offset:36896
	ds_read_b128 v[190:193], v189 offset:32
	s_waitcnt lgkmcnt(5)
	v_mfma_f32_32x32x16_bf16 v[0:15], v[224:227], v[194:197], v[0:15]
	ds_read_b128 v[198:201], v189 offset:4640
	s_waitcnt lgkmcnt(5)
	v_mfma_f32_32x32x16_bf16 v[16:31], v[228:231], v[194:197], v[16:31]
	ds_read_b128 v[224:227], v189 offset:9248
	s_waitcnt lgkmcnt(5)
	v_mfma_f32_32x32x16_bf16 v[34:49], v[232:235], v[194:197], v[34:49]
	ds_read_b128 v[228:231], v189 offset:13856
	s_waitcnt lgkmcnt(5)
	v_mfma_f32_32x32x16_bf16 v[50:65], v[236:239], v[194:197], v[50:65]
	ds_read_b128 v[194:197], v164 offset:36928
	ds_read_b128 v[232:235], v189 offset:64
	s_waitcnt lgkmcnt(5)
	v_mfma_f32_32x32x16_bf16 v[0:15], v[190:193], v[240:243], v[0:15]
	ds_read_b128 v[236:239], v189 offset:4672
	s_waitcnt lgkmcnt(5)
	v_mfma_f32_32x32x16_bf16 v[16:31], v[198:201], v[240:243], v[16:31]
	ds_read_b128 v[190:193], v189 offset:9280
	s_waitcnt lgkmcnt(5)
	v_mfma_f32_32x32x16_bf16 v[34:49], v[224:227], v[240:243], v[34:49]
	s_waitcnt vmcnt(15)
	ds_write_b128 v166, v[130:133] offset:18432
	ds_read_b128 v[198:201], v189 offset:13888
	s_waitcnt lgkmcnt(6)
	v_mfma_f32_32x32x16_bf16 v[50:65], v[228:231], v[240:243], v[50:65]
	s_waitcnt vmcnt(9)
	ds_write_b128 v166, v[138:141] offset:55296
	ds_read_b128 v[240:243], v164 offset:36960
	ds_read_b128 v[224:227], v189 offset:96
	s_waitcnt lgkmcnt(7)
	v_mfma_f32_32x32x16_bf16 v[0:15], v[232:235], v[194:197], v[0:15]
	s_waitcnt vmcnt(13)
	ds_write_b128 v166, v[134:137] offset:23040
	ds_read_b128 v[228:231], v189 offset:4704
	s_waitcnt lgkmcnt(8)
	v_mfma_f32_32x32x16_bf16 v[16:31], v[236:239], v[194:197], v[16:31]
	s_waitcnt vmcnt(12)
	ds_write_b128 v166, v[146:149] offset:59904
	ds_read_b128 v[232:235], v189 offset:9312
	s_waitcnt lgkmcnt(9)
	v_mfma_f32_32x32x16_bf16 v[34:49], v[190:193], v[194:197], v[34:49]
	s_waitcnt vmcnt(11)
	ds_write_b128 v166, v[142:145] offset:27648
	ds_read_b128 v[236:239], v189 offset:13920
	s_waitcnt lgkmcnt(9)
	v_mfma_f32_32x32x16_bf16 v[50:65], v[198:201], v[194:197], v[50:65]
	s_waitcnt vmcnt(10)
	ds_write_b128 v166, v[150:153] offset:64512
	s_waitcnt lgkmcnt(7)
	v_mfma_f32_32x32x16_bf16 v[0:15], v[224:227], v[240:243], v[0:15]
	s_waitcnt vmcnt(9)
	ds_write_b128 v166, v[154:157] offset:32256
	s_waitcnt lgkmcnt(6)
	v_mfma_f32_32x32x16_bf16 v[16:31], v[228:231], v[240:243], v[16:31]
	s_waitcnt vmcnt(8)
	ds_write_b128 v165, v[158:161] offset:13824
	s_setprio 0
	s_waitcnt lgkmcnt(0)
	s_barrier
	v_mfma_f32_32x32x16_bf16 v[34:49], v[232:235], v[240:243], v[34:49]
	v_mfma_f32_32x32x16_bf16 v[50:65], v[236:239], v[240:243], v[50:65]
	s_branch .Lqs1851_join
